# prompt attention loop A: K tile via LDS-DMA + V tile loads, issued at start of half-step (was mid-step into staging VGPRs)
# speedup vs baseline: 1.0155x; 1.0155x over previous
.LBB0_1167:
	v_readfirstlane_b32 s8, v176
	v_lshrrev_b32_e32 v234, 4, v176
	v_lshl_add_u64 v[230:231], v[158:159], 0, v[96:97]
	s_and_b32 s8, s8, 0xfffffc00
	v_and_b32_e32 v234, 0x70, v234
	s_add_i32 m0, s8, 0x8000
	v_xor_b32_e32 v230, v234, v230
	v_lshl_add_u64 v[242:243], v[156:157], 0, v[96:97]
	global_load_lds_dwordx4 v[230:231], off
	v_lshl_add_u64 v[230:231], v[154:155], 0, v[96:97]
	s_add_i32 m0, s8, 0xa000
	v_xor_b32_e32 v230, v234, v230
	v_lshl_add_u64 v[246:247], v[152:153], 0, v[96:97]
	global_load_lds_dwordx4 v[230:231], off
	global_load_dwordx4 v[242:245], v[242:243], off
	global_load_dwordx4 v[246:249], v[246:247], off
	ds_read_b128 v[80:83], v189
	ds_read_b128 v[84:87], v189 offset:32
	ds_read_b128 v[64:67], v189 offset:128
	ds_read_b128 v[68:71], v189 offset:160
	ds_read_b128 v[88:91], v189 offset:64
	ds_read_b128 v[72:75], v189 offset:192
	ds_read_b128 v[92:95], v189 offset:96
	ds_read_b128 v[76:79], v189 offset:224
	ds_read_b128 v[206:209], v181 offset:49152
	ds_read_b128 v[210:213], v181 offset:57344
	v_add_f32_e32 v146, 0, v147
	v_add_f32_e32 v146, v148, v146
	v_add_f32_e32 v146, v149, v146
	s_waitcnt lgkmcnt(1)
	v_mfma_f32_32x32x16_bf16 v[80:95], v[206:209], v[126:129], v[80:95]
	v_add_f32_e32 v146, v202, v146
	v_add_f32_e32 v146, v203, v146
	v_add_f32_e32 v146, v205, v146
	v_add_f32_e32 v146, v201, v146
	v_add_f32_e32 v146, v204, v146
	v_add_f32_e32 v146, v193, v146
	v_add_f32_e32 v146, v195, v146
	s_waitcnt lgkmcnt(0)
	v_mfma_f32_32x32x16_bf16 v[64:79], v[210:213], v[126:129], v[64:79]
	ds_read_b128 v[206:209], v182 offset:49152
	ds_read_b128 v[210:213], v182 offset:57344
	v_add_f32_e32 v146, v196, v146
	v_add_f32_e32 v146, v199, v146
	v_exp_f32_e32 v142, v142
	v_add_f32_e32 v146, v194, v146
	v_exp_f32_e32 v143, v143
	v_add_f32_e32 v146, v197, v146
	s_waitcnt lgkmcnt(1)
	v_mfma_f32_32x32x16_bf16 v[80:95], v[206:209], v[122:125], v[80:95]
	v_exp_f32_e32 v140, v140
	v_add_f32_e32 v146, v198, v146
	v_exp_f32_e32 v141, v141
	v_add_f32_e32 v146, v200, v146
	v_exp_f32_e32 v136, v136
	v_add_f32_e32 v146, v142, v146
	v_exp_f32_e32 v137, v137
	s_waitcnt lgkmcnt(0)
	v_mfma_f32_32x32x16_bf16 v[64:79], v[210:213], v[122:125], v[64:79]
	ds_read_b128 v[206:209], v180 offset:49152
	ds_read_b128 v[210:213], v180 offset:57344
	v_add_f32_e32 v146, v143, v146
	v_exp_f32_e32 v134, v134
	v_add_f32_e32 v146, v140, v146
	v_exp_f32_e32 v135, v135
	v_add_f32_e32 v146, v141, v146
	v_exp_f32_e32 v130, v130
	s_waitcnt lgkmcnt(1)
	v_mfma_f32_32x32x16_bf16 v[80:95], v[206:209], v[118:121], v[80:95]
	v_add_f32_e32 v146, v136, v146
	v_exp_f32_e32 v131, v131
	v_add_f32_e32 v146, v137, v146
	v_exp_f32_e32 v144, v144
	v_add_f32_e32 v146, v134, v146
	v_exp_f32_e32 v145, v145
	v_add_f32_e32 v146, v135, v146
	s_waitcnt lgkmcnt(0)
	v_mfma_f32_32x32x16_bf16 v[64:79], v[210:213], v[118:121], v[64:79]
	ds_read_b128 v[206:209], v151 offset:49152
	ds_read_b128 v[210:213], v151 offset:57344
	v_exp_f32_e32 v138, v138
	v_add_f32_e32 v146, v130, v146
	v_exp_f32_e32 v139, v139
	v_add_f32_e32 v146, v131, v146
	v_exp_f32_e32 v132, v132
	v_add_f32_e32 v146, v144, v146
	s_waitcnt lgkmcnt(1)
	v_mfma_f32_32x32x16_bf16 v[80:95], v[206:209], v[114:117], v[80:95]
	v_exp_f32_e32 v133, v133
	v_add_f32_e32 v146, v145, v146
	v_add_f32_e32 v146, v138, v146
	v_add_f32_e32 v146, v139, v146
	v_add_f32_e32 v146, v132, v146
	v_add_f32_e32 v190, v133, v146
	v_mov_b32_e32 v191, v190
	s_waitcnt lgkmcnt(0)
	v_mfma_f32_32x32x16_bf16 v[64:79], v[210:213], v[114:117], v[64:79]
	ds_read_b128 v[206:209], v181 offset:49280
	ds_read_b128 v[210:213], v181 offset:57472
	v_permlane32_swap_b32_e32 v190, v191
	v_cvt_pk_bf16_f32 v146, v147, v148
	v_cvt_pk_bf16_f32 v147, v149, v202
	v_cvt_pk_bf16_f32 v148, v203, v205
	v_cvt_pk_bf16_f32 v149, v201, v204
	s_waitcnt lgkmcnt(1)
	v_mfma_f32_32x32x16_bf16 v[80:95], v[206:209], v[110:113], v[80:95]
	v_cvt_pk_bf16_f32 v192, v193, v195
	v_cvt_pk_bf16_f32 v193, v196, v199
	v_cvt_pk_bf16_f32 v194, v194, v197
	v_cvt_pk_bf16_f32 v195, v198, v200
	v_cvt_pk_bf16_f32 v196, v142, v143
	v_cvt_pk_bf16_f32 v197, v140, v141
	v_cvt_pk_bf16_f32 v198, v136, v137
	s_waitcnt lgkmcnt(0)
	v_mfma_f32_32x32x16_bf16 v[64:79], v[210:213], v[110:113], v[64:79]
	ds_read_b128 v[206:209], v182 offset:49280
	ds_read_b128 v[210:213], v182 offset:57472
	v_cvt_pk_bf16_f32 v199, v134, v135
	v_cvt_pk_bf16_f32 v200, v130, v131
	v_cvt_pk_bf16_f32 v201, v144, v145
	v_cvt_pk_bf16_f32 v202, v138, v139
	v_cvt_pk_bf16_f32 v203, v132, v133
	v_permlane32_swap_b32_e32 v146, v148
	s_waitcnt lgkmcnt(1)
	v_mfma_f32_32x32x16_bf16 v[80:95], v[206:209], v[106:109], v[80:95]
	v_permlane32_swap_b32_e32 v147, v149
	v_permlane32_swap_b32_e32 v192, v194
	v_permlane32_swap_b32_e32 v193, v195
	v_permlane32_swap_b32_e32 v196, v198
	s_waitcnt lgkmcnt(0)
	v_mfma_f32_32x32x16_bf16 v[64:79], v[210:213], v[106:109], v[64:79]
	ds_read_b128 v[206:209], v180 offset:49280
	ds_read_b128 v[210:213], v180 offset:57472
	v_permlane32_swap_b32_e32 v197, v199
	v_permlane32_swap_b32_e32 v200, v202
	v_permlane32_swap_b32_e32 v201, v203
	s_waitcnt lgkmcnt(1)
	v_mfma_f32_32x32x16_bf16 v[80:95], v[206:209], v[102:105], v[80:95]
	s_waitcnt lgkmcnt(0)
	v_mfma_f32_32x32x16_bf16 v[64:79], v[210:213], v[102:105], v[64:79]
	ds_read_b128 v[206:209], v151 offset:49280
	ds_read_b128 v[210:213], v151 offset:57472
	s_waitcnt lgkmcnt(1)
	v_mfma_f32_32x32x16_bf16 v[80:95], v[206:209], v[98:101], v[80:95]
	s_waitcnt lgkmcnt(0)
	v_mfma_f32_32x32x16_bf16 v[64:79], v[210:213], v[98:101], v[64:79]
	ds_read_b64_tr_b16 v[204:205], v174 offset:0
	ds_read_b64_tr_b16 v[206:207], v174 offset:0x800
	ds_read_b64_tr_b16 v[208:209], v174 offset:0x1000
	ds_read_b64_tr_b16 v[210:211], v174 offset:0x1800
	ds_read_b64_tr_b16 v[220:221], v174 offset:0x2000
	ds_read_b64_tr_b16 v[222:223], v174 offset:0x2800
	ds_read_b64_tr_b16 v[224:225], v174 offset:0x3000
	ds_read_b64_tr_b16 v[226:227], v174 offset:0x3800
	s_waitcnt lgkmcnt(0)
	s_nop 0
	v_mfma_f32_32x32x16_bf16 v[48:63], v[146:149], v[204:207], v[48:63]
	ds_read_b64_tr_b16 v[204:205], v174 offset:0x200
	ds_read_b64_tr_b16 v[206:207], v174 offset:0xa00
	v_mfma_f32_32x32x16_bf16 v[48:63], v[192:195], v[208:211], v[48:63]
	ds_read_b64_tr_b16 v[208:209], v174 offset:0x1200
	ds_read_b64_tr_b16 v[210:211], v174 offset:0x1a00
	v_mfma_f32_32x32x16_bf16 v[48:63], v[196:199], v[220:223], v[48:63]
	ds_read_b64_tr_b16 v[220:221], v174 offset:0x2200
	ds_read_b64_tr_b16 v[222:223], v174 offset:0x2a00
	v_mfma_f32_32x32x16_bf16 v[48:63], v[200:203], v[224:227], v[48:63]
	ds_read_b64_tr_b16 v[224:225], v174 offset:0x3200
	ds_read_b64_tr_b16 v[226:227], v174 offset:0x3a00
	s_waitcnt lgkmcnt(0)
	v_mfma_f32_32x32x16_bf16 v[32:47], v[146:149], v[204:207], v[32:47]
	ds_read_b64_tr_b16 v[204:205], v174 offset:0x400
	ds_read_b64_tr_b16 v[206:207], v174 offset:0xc00
	v_mfma_f32_32x32x16_bf16 v[32:47], v[192:195], v[208:211], v[32:47]
	ds_read_b64_tr_b16 v[208:209], v174 offset:0x1400
	ds_read_b64_tr_b16 v[210:211], v174 offset:0x1c00
	v_mfma_f32_32x32x16_bf16 v[32:47], v[196:199], v[220:223], v[32:47]
	ds_read_b64_tr_b16 v[220:221], v174 offset:0x2400
	ds_read_b64_tr_b16 v[222:223], v174 offset:0x2c00
	v_mfma_f32_32x32x16_bf16 v[32:47], v[200:203], v[224:227], v[32:47]
	ds_read_b64_tr_b16 v[224:225], v174 offset:0x3400
	ds_read_b64_tr_b16 v[226:227], v174 offset:0x3c00
	s_waitcnt lgkmcnt(0)
	v_mfma_f32_32x32x16_bf16 v[16:31], v[146:149], v[204:207], v[16:31]
	ds_read_b64_tr_b16 v[204:205], v174 offset:0x600
	ds_read_b64_tr_b16 v[206:207], v174 offset:0xe00
	v_mfma_f32_32x32x16_bf16 v[16:31], v[192:195], v[208:211], v[16:31]
	ds_read_b64_tr_b16 v[208:209], v174 offset:0x1600
	ds_read_b64_tr_b16 v[210:211], v174 offset:0x1e00
	v_mfma_f32_32x32x16_bf16 v[16:31], v[196:199], v[220:223], v[16:31]
	ds_read_b64_tr_b16 v[220:221], v174 offset:0x2600
	ds_read_b64_tr_b16 v[222:223], v174 offset:0x2e00
	v_mfma_f32_32x32x16_bf16 v[16:31], v[200:203], v[224:227], v[16:31]
	ds_read_b64_tr_b16 v[224:225], v174 offset:0x3600
	ds_read_b64_tr_b16 v[226:227], v174 offset:0x3e00
	s_waitcnt lgkmcnt(0)
	v_mfma_f32_32x32x16_bf16 v[0:15], v[146:149], v[204:207], v[0:15]
	s_sub_i32 s6, s92, 64
	s_cmp_le_i32 s6, s41
	v_mfma_f32_32x32x16_bf16 v[0:15], v[192:195], v[208:211], v[0:15]
	v_mfma_f32_32x32x16_bf16 v[0:15], v[196:199], v[220:223], v[0:15]
	v_mfma_f32_32x32x16_bf16 v[0:15], v[200:203], v[224:227], v[0:15]
	s_cbranch_scc1 .LBB0_1169
	v_add_u32_e32 v146, 64, v188
	v_cmp_gt_i32_e64 s[66:67], 26, v146
	v_cmp_gt_i32_e64 s[68:69], 27, v146
	v_cmp_gt_i32_e64 s[64:65], 25, v146
	s_and_b64 s[66:67], s[68:69], s[66:67]
	v_cmp_gt_i32_e64 s[62:63], 24, v146
	s_and_b64 s[64:65], s[66:67], s[64:65]
	v_cmp_gt_i32_e64 s[60:61], 19, v146
	s_and_b64 s[62:63], s[64:65], s[62:63]
	v_cmp_gt_i32_e64 s[58:59], 18, v146
	s_and_b64 s[60:61], s[62:63], s[60:61]
	v_cmp_gt_i32_e64 s[56:57], 17, v146
	s_and_b64 s[58:59], s[60:61], s[58:59]
	v_cmp_gt_i32_e64 s[54:55], 16, v146
	s_and_b64 s[56:57], s[58:59], s[56:57]
	v_cmp_gt_i32_e64 s[52:53], 11, v146
	s_and_b64 s[54:55], s[56:57], s[54:55]
	v_cmp_gt_i32_e64 s[50:51], 10, v146
	s_and_b64 s[52:53], s[54:55], s[52:53]
	v_cmp_gt_i32_e64 s[48:49], 9, v146
	s_and_b64 s[50:51], s[52:53], s[50:51]
	v_cmp_gt_i32_e64 s[46:47], 8, v146
	s_and_b64 s[48:49], s[50:51], s[48:49]
	v_cmp_gt_i32_e64 s[44:45], 3, v146
	s_and_b64 s[46:47], s[48:49], s[46:47]
	v_cmp_gt_i32_e64 s[42:43], 2, v146
	s_and_b64 s[44:45], s[46:47], s[44:45]
	v_cmp_gt_i32_e64 s[38:39], 1, v146
	s_and_b64 s[42:43], s[44:45], s[42:43]
	v_cmp_gt_i32_e64 s[36:37], 0, v146
	s_and_b64 s[38:39], s[42:43], s[38:39]
	s_and_b64 s[36:37], s[38:39], s[36:37]
	v_cmp_gt_i32_e64 s[34:35], 58, v146
	v_cndmask_b32_e64 v80, v80, v232, s[36:37]
	v_cmp_gt_i32_e64 s[36:37], 59, v146
	v_cmp_gt_i32_e64 s[30:31], 57, v146
	s_and_b64 s[34:35], s[36:37], s[34:35]
	v_cmp_gt_i32_e64 s[28:29], 56, v146
	s_and_b64 s[30:31], s[34:35], s[30:31]
	v_cmp_gt_i32_e64 s[26:27], 51, v146
	s_and_b64 s[28:29], s[30:31], s[28:29]
	v_cmp_gt_i32_e64 s[24:25], 50, v146
	s_and_b64 s[26:27], s[28:29], s[26:27]
	v_cmp_gt_i32_e64 s[22:23], 49, v146
	s_and_b64 s[24:25], s[26:27], s[24:25]
	v_cmp_gt_i32_e64 s[20:21], 48, v146
	s_and_b64 s[22:23], s[24:25], s[22:23]
	v_cmp_gt_i32_e64 s[18:19], 43, v146
	s_and_b64 s[20:21], s[22:23], s[20:21]
	v_cmp_gt_i32_e64 s[16:17], 42, v146
	s_and_b64 s[18:19], s[20:21], s[18:19]
	v_cmp_gt_i32_e64 s[14:15], 41, v146
	s_and_b64 s[16:17], s[18:19], s[16:17]
	v_cmp_gt_i32_e64 s[12:13], 40, v146
	s_and_b64 s[14:15], s[16:17], s[14:15]
	v_cmp_gt_i32_e64 s[10:11], 35, v146
	s_and_b64 s[12:13], s[14:15], s[12:13]
	v_cmp_gt_i32_e64 s[8:9], 34, v146
	s_and_b64 s[10:11], s[12:13], s[10:11]
	v_cmp_gt_i32_e64 s[6:7], 33, v146
	s_and_b64 s[8:9], s[10:11], s[8:9]
	v_cmp_gt_i32_e32 vcc, 32, v146
	s_and_b64 s[6:7], s[8:9], s[6:7]
	s_and_b64 vcc, s[6:7], vcc
	v_cndmask_b32_e64 v95, v95, v232, s[68:69]
	v_cndmask_b32_e64 v94, v94, v232, s[66:67]
	v_cndmask_b32_e64 v93, v93, v232, s[64:65]
	v_cndmask_b32_e64 v92, v92, v232, s[62:63]
	v_cndmask_b32_e64 v91, v91, v232, s[60:61]
	v_cndmask_b32_e64 v90, v90, v232, s[58:59]
	v_cndmask_b32_e64 v89, v89, v232, s[56:57]
	v_cndmask_b32_e64 v88, v88, v232, s[54:55]
	v_cndmask_b32_e64 v87, v87, v232, s[52:53]
	v_cndmask_b32_e64 v86, v86, v232, s[50:51]
	v_cndmask_b32_e64 v85, v85, v232, s[48:49]
	v_cndmask_b32_e64 v84, v84, v232, s[46:47]
	v_cndmask_b32_e64 v83, v83, v232, s[44:45]
	v_cndmask_b32_e64 v82, v82, v232, s[42:43]
	v_cndmask_b32_e64 v81, v81, v232, s[38:39]
	v_cndmask_b32_e64 v79, v79, v232, s[36:37]
	v_cndmask_b32_e64 v78, v78, v232, s[34:35]
	v_cndmask_b32_e64 v77, v77, v232, s[30:31]
	v_cndmask_b32_e64 v76, v76, v232, s[28:29]
	v_cndmask_b32_e64 v75, v75, v232, s[26:27]
	v_cndmask_b32_e64 v74, v74, v232, s[24:25]
	v_cndmask_b32_e64 v73, v73, v232, s[22:23]
	v_cndmask_b32_e64 v72, v72, v232, s[20:21]
	v_cndmask_b32_e64 v71, v71, v232, s[18:19]
	v_cndmask_b32_e64 v70, v70, v232, s[16:17]
	v_cndmask_b32_e64 v69, v69, v232, s[14:15]
	v_cndmask_b32_e64 v68, v68, v232, s[12:13]
	v_cndmask_b32_e64 v67, v67, v232, s[10:11]
	v_cndmask_b32_e64 v66, v66, v232, s[8:9]
	v_cndmask_b32_e64 v65, v65, v232, s[6:7]
	v_cndmask_b32_e32 v64, v64, v232, vcc
.LBB0_1169:
	v_max_f32_e32 v146, v81, v81
	v_max_f32_e32 v147, v80, v80
	v_max_f32_e32 v146, v147, v146
	v_max3_f32 v146, v146, v82, v83
	v_max3_f32 v146, v146, v84, v85
	v_max3_f32 v146, v146, v86, v87
	v_max3_f32 v146, v146, v88, v89
	v_max3_f32 v146, v146, v90, v91
	v_max3_f32 v146, v146, v92, v93
	v_max3_f32 v146, v146, v94, v95
	v_max3_f32 v146, v146, v64, v65
	v_max3_f32 v146, v146, v66, v67
	v_max3_f32 v146, v146, v68, v69
	v_max3_f32 v146, v146, v70, v71
	v_max3_f32 v146, v146, v72, v73
	v_max3_f32 v146, v146, v74, v75
	v_max3_f32 v146, v146, v76, v77
	v_max3_f32 v146, v146, v78, v79
	v_mov_b32_e32 v147, v146
	s_nop 1
	v_permlane32_swap_b32_e32 v146, v147
	v_max_f32_e32 v147, v147, v147
	v_max_f32_e32 v146, v146, v146
	v_max_f32_e32 v146, v146, v147
	v_sub_f32_e32 v147, v146, v187
	v_mul_f32_e32 v147, 0x3db504f3, v147
	s_mov_b32 s6, 0x41000000
	v_cmp_ge_f32_e32 vcc, s6, v147
	v_max_f32_e32 v147, v187, v187
	v_max_f32_e32 v146, v147, v146
	v_sub_f32_e32 v147, v187, v146
	v_mul_f32_e32 v147, 0x3e0293ee, v147
	v_exp_f32_e32 v147, v147
	s_cmp_eq_u64 vcc, exec
	s_cselect_b64 s[6:7], -1, 0
	s_barrier
	s_waitcnt vmcnt(0)
	v_cndmask_b32_e64 v192, v147, 1.0, s[6:7]
	v_cmp_gt_f32_e32 vcc, 1.0, v192
	s_waitcnt vmcnt(0)
	ds_write_b128 v184, v[242:245]
	ds_write_b128 v185, v[246:249]
	s_cbranch_vccz .LBB0_1173
	s_and_saveexec_b64 s[8:9], s[4:5]
	ds_write_b32 v173, v192 offset:128
	s_or_b64 exec, exec, s[8:9]
	s_waitcnt lgkmcnt(0)
	ds_read_b128 v[130:133], v169 offset:224
	ds_read_b128 v[134:137], v169 offset:192
	ds_read_b128 v[138:141], v169 offset:160
	ds_read_b128 v[142:145], v169 offset:128
	s_waitcnt lgkmcnt(3)
	v_pk_mul_f32 v[62:63], v[62:63], v[132:133]
	s_waitcnt lgkmcnt(2)
	v_pk_mul_f32 v[58:59], v[58:59], v[136:137]
	s_waitcnt lgkmcnt(1)
	v_pk_mul_f32 v[54:55], v[54:55], v[140:141]
	s_waitcnt lgkmcnt(0)
	v_pk_mul_f32 v[50:51], v[50:51], v[144:145]
	v_pk_mul_f32 v[60:61], v[60:61], v[130:131]
	v_pk_mul_f32 v[56:57], v[56:57], v[134:135]
	v_pk_mul_f32 v[52:53], v[52:53], v[138:139]
	v_pk_mul_f32 v[48:49], v[48:49], v[142:143]
	v_pk_mul_f32 v[46:47], v[46:47], v[132:133]
	v_pk_mul_f32 v[42:43], v[42:43], v[136:137]
	v_pk_mul_f32 v[38:39], v[38:39], v[140:141]
	v_pk_mul_f32 v[34:35], v[34:35], v[144:145]
	v_pk_mul_f32 v[44:45], v[44:45], v[130:131]
	v_pk_mul_f32 v[40:41], v[40:41], v[134:135]
	v_pk_mul_f32 v[36:37], v[36:37], v[138:139]
	v_pk_mul_f32 v[32:33], v[32:33], v[142:143]
	v_pk_mul_f32 v[30:31], v[30:31], v[132:133]
	v_pk_mul_f32 v[26:27], v[26:27], v[136:137]
	v_pk_mul_f32 v[22:23], v[22:23], v[140:141]
	v_pk_mul_f32 v[18:19], v[18:19], v[144:145]
	v_pk_mul_f32 v[28:29], v[28:29], v[130:131]
	v_pk_mul_f32 v[24:25], v[24:25], v[134:135]
	v_pk_mul_f32 v[20:21], v[20:21], v[138:139]
	v_pk_mul_f32 v[16:17], v[16:17], v[142:143]
	v_pk_mul_f32 v[14:15], v[14:15], v[132:133]
	v_pk_mul_f32 v[10:11], v[10:11], v[136:137]
	v_pk_mul_f32 v[6:7], v[6:7], v[140:141]
	v_pk_mul_f32 v[2:3], v[2:3], v[144:145]
	v_pk_mul_f32 v[12:13], v[12:13], v[130:131]
	v_pk_mul_f32 v[8:9], v[8:9], v[134:135]
	v_pk_mul_f32 v[4:5], v[4:5], v[138:139]
	v_pk_mul_f32 v[0:1], v[0:1], v[142:143]
.LBB0_1173:
	v_cndmask_b32_e64 v187, v146, v187, s[6:7]
	v_mul_f32_e32 v146, 0xbe0293ee, v187
	v_fmamk_f32 v80, v80, 0x3e0293ee, v146
	v_fmamk_f32 v81, v81, 0x3e0293ee, v146
	v_fmamk_f32 v82, v82, 0x3e0293ee, v146
	v_fmamk_f32 v83, v83, 0x3e0293ee, v146
	v_fmamk_f32 v84, v84, 0x3e0293ee, v146
	v_fmamk_f32 v85, v85, 0x3e0293ee, v146
	v_fmamk_f32 v86, v86, 0x3e0293ee, v146
	v_fmamk_f32 v87, v87, 0x3e0293ee, v146
	v_fmamk_f32 v88, v88, 0x3e0293ee, v146
	v_fmamk_f32 v89, v89, 0x3e0293ee, v146
	v_fmamk_f32 v90, v90, 0x3e0293ee, v146
	v_fmamk_f32 v91, v91, 0x3e0293ee, v146
	v_fmamk_f32 v92, v92, 0x3e0293ee, v146
	v_fmamk_f32 v93, v93, 0x3e0293ee, v146
	v_fmamk_f32 v94, v94, 0x3e0293ee, v146
	v_fmamk_f32 v95, v95, 0x3e0293ee, v146
	v_exp_f32_e32 v139, v80
	v_exp_f32_e32 v141, v81
	v_exp_f32_e32 v142, v82
	v_exp_f32_e32 v143, v83
	v_exp_f32_e32 v144, v84
	v_exp_f32_e32 v145, v85
	v_exp_f32_e32 v138, v86
	v_exp_f32_e32 v140, v87
	v_exp_f32_e32 v133, v88
	v_exp_f32_e32 v135, v89
	v_exp_f32_e32 v136, v90
	v_exp_f32_e32 v137, v91
	v_exp_f32_e32 v130, v92
	v_exp_f32_e32 v131, v93
	v_exp_f32_e32 v132, v94
	v_exp_f32_e32 v134, v95
	v_fmamk_f32 v198, v64, 0x3e0293ee, v146
	v_fmamk_f32 v199, v65, 0x3e0293ee, v146
	v_fmamk_f32 v200, v66, 0x3e0293ee, v146
	v_fmamk_f32 v201, v67, 0x3e0293ee, v146
	v_fmamk_f32 v202, v68, 0x3e0293ee, v146
	v_fmamk_f32 v148, v69, 0x3e0293ee, v146
	v_fmamk_f32 v149, v70, 0x3e0293ee, v146
	v_fmamk_f32 v193, v71, 0x3e0293ee, v146
	v_fmamk_f32 v194, v72, 0x3e0293ee, v146
	v_fmamk_f32 v195, v73, 0x3e0293ee, v146
	v_fmamk_f32 v196, v74, 0x3e0293ee, v146
	v_fmamk_f32 v197, v75, 0x3e0293ee, v146
	v_fmamk_f32 v147, v76, 0x3e0293ee, v146
	v_fmamk_f32 v203, v77, 0x3e0293ee, v146
	v_fmamk_f32 v204, v78, 0x3e0293ee, v146
	v_fmac_f32_e32 v146, 0x3e0293ee, v79
	s_waitcnt lgkmcnt(0)
	s_barrier
	v_readfirstlane_b32 s8, v176
	v_lshrrev_b32_e32 v234, 4, v176
	v_lshl_add_u64 v[230:231], v[166:167], 0, v[96:97]
	s_and_b32 s8, s8, 0xfffffc00
	v_and_b32_e32 v234, 0x70, v234
	s_add_i32 m0, s8, 0xc000
	v_xor_b32_e32 v230, v234, v230
	v_lshl_add_u64 v[242:243], v[164:165], 0, v[96:97]
	global_load_lds_dwordx4 v[230:231], off
	v_lshl_add_u64 v[230:231], v[162:163], 0, v[96:97]
	s_add_i32 m0, s8, 0xe000
	v_xor_b32_e32 v230, v234, v230
	v_lshl_add_u64 v[246:247], v[160:161], 0, v[96:97]
	global_load_lds_dwordx4 v[230:231], off
	global_load_dwordx4 v[242:245], v[242:243], off
	global_load_dwordx4 v[246:249], v[246:247], off
	ds_read_b128 v[80:83], v189 offset:256
	ds_read_b128 v[84:87], v189 offset:288
	ds_read_b128 v[64:67], v189 offset:384
	ds_read_b128 v[68:71], v189 offset:416
	ds_read_b128 v[88:91], v189 offset:320
	ds_read_b128 v[72:75], v189 offset:448
	ds_read_b128 v[92:95], v189 offset:352
	ds_read_b128 v[76:79], v189 offset:480
	ds_read_b128 v[206:209], v181 offset:32768
	ds_read_b128 v[210:213], v181 offset:40960
	v_exp_f32_e32 v218, v146
	v_add_f32_e32 v146, 0, v139
	v_add_f32_e32 v146, v141, v146
	s_waitcnt lgkmcnt(1)
	v_mfma_f32_32x32x16_bf16 v[80:95], v[206:209], v[126:129], v[80:95]
	v_add_f32_e32 v146, v142, v146
	v_add_f32_e32 v146, v143, v146
	v_add_f32_e32 v146, v144, v146
	v_add_f32_e32 v146, v145, v146
	v_add_f32_e32 v146, v138, v146
	v_add_f32_e32 v146, v140, v146
	v_add_f32_e32 v146, v133, v146
	s_waitcnt lgkmcnt(0)
	v_mfma_f32_32x32x16_bf16 v[64:79], v[210:213], v[126:129], v[64:79]
	ds_read_b128 v[206:209], v182 offset:32768
	ds_read_b128 v[210:213], v182 offset:40960
	v_add_f32_e32 v146, v135, v146
	v_add_f32_e32 v146, v136, v146
	v_add_f32_e32 v146, v137, v146
	v_exp_f32_e32 v198, v198
	v_add_f32_e32 v146, v130, v146
	v_exp_f32_e32 v199, v199
	s_waitcnt lgkmcnt(1)
	v_mfma_f32_32x32x16_bf16 v[80:95], v[206:209], v[122:125], v[80:95]
	v_add_f32_e32 v146, v131, v146
	v_exp_f32_e32 v200, v200
	v_add_f32_e32 v146, v132, v146
	v_exp_f32_e32 v201, v201
	v_add_f32_e32 v146, v134, v146
	v_exp_f32_e32 v202, v202
	v_add_f32_e32 v146, v198, v146
	s_waitcnt lgkmcnt(0)
	v_mfma_f32_32x32x16_bf16 v[64:79], v[210:213], v[122:125], v[64:79]
	ds_read_b128 v[206:209], v180 offset:32768
	ds_read_b128 v[210:213], v180 offset:40960
	v_exp_f32_e32 v205, v148
	v_add_f32_e32 v146, v199, v146
	v_add_f32_e32 v146, v200, v146
	v_exp_f32_e32 v193, v193
	v_add_f32_e32 v146, v201, v146
	v_add_f32_e32 v146, v202, v146
	s_waitcnt lgkmcnt(1)
	v_mfma_f32_32x32x16_bf16 v[80:95], v[206:209], v[118:121], v[80:95]
	v_add_f32_e32 v146, v205, v146
	v_exp_f32_e32 v214, v203
	v_exp_f32_e32 v215, v204
	v_cvt_pk_bf16_f32 v148, v144, v145
	v_cvt_pk_bf16_f32 v198, v198, v199
	v_cvt_pk_bf16_f32 v199, v200, v201
	v_cvt_pk_bf16_f32 v200, v202, v205
	s_waitcnt lgkmcnt(0)
	v_mfma_f32_32x32x16_bf16 v[64:79], v[210:213], v[118:121], v[64:79]
	ds_read_b128 v[206:209], v151 offset:32768
	ds_read_b128 v[210:213], v151 offset:40960
	v_cvt_pk_bf16_f32 v205, v215, v218
	v_permlane32_swap_b32_e32 v198, v200
	s_waitcnt lgkmcnt(1)
	v_mfma_f32_32x32x16_bf16 v[80:95], v[206:209], v[114:117], v[80:95]
	s_waitcnt lgkmcnt(0)
	v_mfma_f32_32x32x16_bf16 v[64:79], v[210:213], v[114:117], v[64:79]
	ds_read_b128 v[206:209], v181 offset:32896
	ds_read_b128 v[210:213], v181 offset:41088
	s_waitcnt lgkmcnt(1)
	v_mfma_f32_32x32x16_bf16 v[80:95], v[206:209], v[110:113], v[80:95]
	s_waitcnt lgkmcnt(0)
	v_mfma_f32_32x32x16_bf16 v[64:79], v[210:213], v[110:113], v[64:79]
	ds_read_b128 v[206:209], v182 offset:32896
	ds_read_b128 v[210:213], v182 offset:41088
	s_waitcnt lgkmcnt(1)
	v_mfma_f32_32x32x16_bf16 v[80:95], v[206:209], v[106:109], v[80:95]
	s_waitcnt lgkmcnt(0)
	v_mfma_f32_32x32x16_bf16 v[64:79], v[210:213], v[106:109], v[64:79]
	ds_read_b128 v[206:209], v180 offset:32896
	ds_read_b128 v[210:213], v180 offset:41088
	s_waitcnt lgkmcnt(1)
	v_mfma_f32_32x32x16_bf16 v[80:95], v[206:209], v[102:105], v[80:95]
	s_waitcnt lgkmcnt(0)
	v_mfma_f32_32x32x16_bf16 v[64:79], v[210:213], v[102:105], v[64:79]
	ds_read_b128 v[206:209], v151 offset:32896
	ds_read_b128 v[210:213], v151 offset:41088
	s_waitcnt lgkmcnt(1)
	v_mfma_f32_32x32x16_bf16 v[80:95], v[206:209], v[98:101], v[80:95]
	v_exp_f32_e32 v208, v149
	v_exp_f32_e32 v209, v194
	v_cvt_pk_bf16_f32 v149, v138, v140
	v_cvt_pk_bf16_f32 v194, v133, v135
	v_add_f32_e32 v146, v208, v146
	v_add_f32_e32 v146, v193, v146
	v_add_f32_e32 v146, v209, v146
	s_waitcnt lgkmcnt(0)
	v_mfma_f32_32x32x16_bf16 v[64:79], v[210:213], v[98:101], v[64:79]
	v_exp_f32_e32 v210, v195
	v_exp_f32_e32 v211, v196
	v_exp_f32_e32 v212, v197
	v_exp_f32_e32 v213, v147
	v_add_f32_e32 v146, v210, v146
	v_add_f32_e32 v146, v211, v146
	v_add_f32_e32 v146, v212, v146
	v_add_f32_e32 v146, v213, v146
	v_add_f32_e32 v146, v214, v146
	v_add_f32_e32 v146, v215, v146
	v_add_f32_e32 v206, v218, v146
	v_mov_b32_e32 v207, v206
	s_nop 1
	v_permlane32_swap_b32_e32 v206, v207
	v_cvt_pk_bf16_f32 v146, v139, v141
	v_cvt_pk_bf16_f32 v147, v142, v143
	v_cvt_pk_bf16_f32 v195, v136, v137
	v_cvt_pk_bf16_f32 v196, v130, v131
	v_cvt_pk_bf16_f32 v197, v132, v134
	v_cvt_pk_bf16_f32 v201, v208, v193
	v_cvt_pk_bf16_f32 v202, v209, v210
	v_cvt_pk_bf16_f32 v203, v211, v212
	v_cvt_pk_bf16_f32 v204, v213, v214
	v_permlane32_swap_b32_e32 v146, v148
	v_permlane32_swap_b32_e32 v147, v149
	v_permlane32_swap_b32_e32 v194, v196
	v_permlane32_swap_b32_e32 v195, v197
	v_permlane32_swap_b32_e32 v199, v201
	v_permlane32_swap_b32_e32 v202, v204
	v_permlane32_swap_b32_e32 v203, v205
	ds_read_b64_tr_b16 v[208:209], v174 offset:0x4000
	ds_read_b64_tr_b16 v[210:211], v174 offset:0x4800
	ds_read_b64_tr_b16 v[220:221], v174 offset:0x5000
	ds_read_b64_tr_b16 v[222:223], v174 offset:0x5800
	ds_read_b64_tr_b16 v[224:225], v174 offset:0x6000
	ds_read_b64_tr_b16 v[226:227], v174 offset:0x6800
	ds_read_b64_tr_b16 v[238:239], v174 offset:0x7000
	ds_read_b64_tr_b16 v[240:241], v174 offset:0x7800
	s_waitcnt lgkmcnt(0)
	s_nop 0
	v_mfma_f32_32x32x16_bf16 v[48:63], v[146:149], v[208:211], v[48:63]
	ds_read_b64_tr_b16 v[208:209], v174 offset:0x4200
	ds_read_b64_tr_b16 v[210:211], v174 offset:0x4a00
	v_mfma_f32_32x32x16_bf16 v[48:63], v[194:197], v[220:223], v[48:63]
	ds_read_b64_tr_b16 v[220:221], v174 offset:0x5200
	ds_read_b64_tr_b16 v[222:223], v174 offset:0x5a00
	v_mfma_f32_32x32x16_bf16 v[48:63], v[198:201], v[224:227], v[48:63]
	ds_read_b64_tr_b16 v[224:225], v174 offset:0x6200
	ds_read_b64_tr_b16 v[226:227], v174 offset:0x6a00
	v_mfma_f32_32x32x16_bf16 v[48:63], v[202:205], v[238:241], v[48:63]
	ds_read_b64_tr_b16 v[238:239], v174 offset:0x7200
	ds_read_b64_tr_b16 v[240:241], v174 offset:0x7a00
	s_waitcnt lgkmcnt(0)
	v_mfma_f32_32x32x16_bf16 v[32:47], v[146:149], v[208:211], v[32:47]
	ds_read_b64_tr_b16 v[208:209], v174 offset:0x4400
	ds_read_b64_tr_b16 v[210:211], v174 offset:0x4c00
	v_mfma_f32_32x32x16_bf16 v[32:47], v[194:197], v[220:223], v[32:47]
	ds_read_b64_tr_b16 v[220:221], v174 offset:0x5400
	ds_read_b64_tr_b16 v[222:223], v174 offset:0x5c00
	v_mfma_f32_32x32x16_bf16 v[32:47], v[198:201], v[224:227], v[32:47]
	ds_read_b64_tr_b16 v[224:225], v174 offset:0x6400
	ds_read_b64_tr_b16 v[226:227], v174 offset:0x6c00
	v_mfma_f32_32x32x16_bf16 v[32:47], v[202:205], v[238:241], v[32:47]
	ds_read_b64_tr_b16 v[238:239], v174 offset:0x7400
	ds_read_b64_tr_b16 v[240:241], v174 offset:0x7c00
	s_waitcnt lgkmcnt(0)
	v_mfma_f32_32x32x16_bf16 v[16:31], v[146:149], v[208:211], v[16:31]
	ds_read_b64_tr_b16 v[208:209], v174 offset:0x4600
	ds_read_b64_tr_b16 v[210:211], v174 offset:0x4e00
	v_mfma_f32_32x32x16_bf16 v[16:31], v[194:197], v[220:223], v[16:31]
	ds_read_b64_tr_b16 v[220:221], v174 offset:0x5600
	ds_read_b64_tr_b16 v[222:223], v174 offset:0x5e00
	v_mfma_f32_32x32x16_bf16 v[16:31], v[198:201], v[224:227], v[16:31]
	ds_read_b64_tr_b16 v[224:225], v174 offset:0x6600
	ds_read_b64_tr_b16 v[226:227], v174 offset:0x6e00
	v_mfma_f32_32x32x16_bf16 v[16:31], v[202:205], v[238:241], v[16:31]
	ds_read_b64_tr_b16 v[238:239], v174 offset:0x7600
	ds_read_b64_tr_b16 v[240:241], v174 offset:0x7e00
	s_waitcnt lgkmcnt(0)
	v_mfma_f32_32x32x16_bf16 v[0:15], v[146:149], v[208:211], v[0:15]
	s_cmp_le_i32 s92, s41
	v_mfma_f32_32x32x16_bf16 v[0:15], v[194:197], v[220:223], v[0:15]
	v_mfma_f32_32x32x16_bf16 v[0:15], v[198:201], v[224:227], v[0:15]
	v_mfma_f32_32x32x16_bf16 v[0:15], v[202:205], v[238:241], v[0:15]
	s_cbranch_scc1 .LBB0_1175
	v_cmp_gt_i32_e64 s[66:67], 26, v188
	v_cmp_gt_i32_e64 s[68:69], 27, v188
	v_cmp_gt_i32_e64 s[64:65], 25, v188
	s_and_b64 s[66:67], s[68:69], s[66:67]
	v_cmp_gt_i32_e64 s[62:63], 24, v188
	s_and_b64 s[64:65], s[66:67], s[64:65]
	v_cmp_gt_i32_e64 s[60:61], 19, v188
	s_and_b64 s[62:63], s[64:65], s[62:63]
	v_cmp_gt_i32_e64 s[58:59], 18, v188
	s_and_b64 s[60:61], s[62:63], s[60:61]
	v_cmp_gt_i32_e64 s[56:57], 17, v188
	s_and_b64 s[58:59], s[60:61], s[58:59]
	v_cmp_gt_i32_e64 s[54:55], 16, v188
	s_and_b64 s[56:57], s[58:59], s[56:57]
	v_cmp_gt_i32_e64 s[52:53], 11, v188
	s_and_b64 s[54:55], s[56:57], s[54:55]
	v_cmp_gt_i32_e64 s[50:51], 10, v188
	s_and_b64 s[52:53], s[54:55], s[52:53]
	v_cmp_gt_i32_e64 s[48:49], 9, v188
	s_and_b64 s[50:51], s[52:53], s[50:51]
	v_cmp_gt_i32_e64 s[46:47], 8, v188
	s_and_b64 s[48:49], s[50:51], s[48:49]
	v_cmp_gt_i32_e64 s[44:45], 3, v188
	s_and_b64 s[46:47], s[48:49], s[46:47]
	v_cmp_gt_i32_e64 s[42:43], 2, v188
	s_and_b64 s[44:45], s[46:47], s[44:45]
	v_cmp_gt_i32_e64 s[38:39], 1, v188
	s_and_b64 s[42:43], s[44:45], s[42:43]
	v_cmp_gt_i32_e64 s[36:37], 0, v188
	s_and_b64 s[38:39], s[42:43], s[38:39]
	s_and_b64 s[36:37], s[38:39], s[36:37]
	v_cmp_gt_i32_e64 s[34:35], 58, v188
	v_cndmask_b32_e64 v80, v80, v232, s[36:37]
	v_cmp_gt_i32_e64 s[36:37], 59, v188
	v_cmp_gt_i32_e64 s[30:31], 57, v188
	s_and_b64 s[34:35], s[36:37], s[34:35]
	v_cmp_gt_i32_e64 s[28:29], 56, v188
	s_and_b64 s[30:31], s[34:35], s[30:31]
	v_cmp_gt_i32_e64 s[26:27], 51, v188
	s_and_b64 s[28:29], s[30:31], s[28:29]
	v_cmp_gt_i32_e64 s[24:25], 50, v188
	s_and_b64 s[26:27], s[28:29], s[26:27]
	v_cmp_gt_i32_e64 s[22:23], 49, v188
	s_and_b64 s[24:25], s[26:27], s[24:25]
	v_cmp_gt_i32_e64 s[20:21], 48, v188
	s_and_b64 s[22:23], s[24:25], s[22:23]
	v_cmp_gt_i32_e64 s[18:19], 43, v188
	s_and_b64 s[20:21], s[22:23], s[20:21]
	v_cmp_gt_i32_e64 s[16:17], 42, v188
	s_and_b64 s[18:19], s[20:21], s[18:19]
	v_cmp_gt_i32_e64 s[14:15], 41, v188
	s_and_b64 s[16:17], s[18:19], s[16:17]
	v_cmp_gt_i32_e64 s[12:13], 40, v188
	s_and_b64 s[14:15], s[16:17], s[14:15]
	v_cmp_gt_i32_e64 s[10:11], 35, v188
	s_and_b64 s[12:13], s[14:15], s[12:13]
	v_cmp_gt_i32_e64 s[8:9], 34, v188
	s_and_b64 s[10:11], s[12:13], s[10:11]
	v_cmp_gt_i32_e64 s[6:7], 33, v188
	s_and_b64 s[8:9], s[10:11], s[8:9]
	v_cmp_gt_i32_e32 vcc, 32, v188
	s_and_b64 s[6:7], s[8:9], s[6:7]
	s_and_b64 vcc, s[6:7], vcc
	v_cndmask_b32_e64 v95, v95, v232, s[68:69]
	v_cndmask_b32_e64 v94, v94, v232, s[66:67]
	v_cndmask_b32_e64 v93, v93, v232, s[64:65]
	v_cndmask_b32_e64 v92, v92, v232, s[62:63]
	v_cndmask_b32_e64 v91, v91, v232, s[60:61]
	v_cndmask_b32_e64 v90, v90, v232, s[58:59]
	v_cndmask_b32_e64 v89, v89, v232, s[56:57]
	v_cndmask_b32_e64 v88, v88, v232, s[54:55]
	v_cndmask_b32_e64 v87, v87, v232, s[52:53]
	v_cndmask_b32_e64 v86, v86, v232, s[50:51]
	v_cndmask_b32_e64 v85, v85, v232, s[48:49]
	v_cndmask_b32_e64 v84, v84, v232, s[46:47]
	v_cndmask_b32_e64 v83, v83, v232, s[44:45]
	v_cndmask_b32_e64 v82, v82, v232, s[42:43]
	v_cndmask_b32_e64 v81, v81, v232, s[38:39]
	v_cndmask_b32_e64 v79, v79, v232, s[36:37]
	v_cndmask_b32_e64 v78, v78, v232, s[34:35]
	v_cndmask_b32_e64 v77, v77, v232, s[30:31]
	v_cndmask_b32_e64 v76, v76, v232, s[28:29]
	v_cndmask_b32_e64 v75, v75, v232, s[26:27]
	v_cndmask_b32_e64 v74, v74, v232, s[24:25]
	v_cndmask_b32_e64 v73, v73, v232, s[22:23]
	v_cndmask_b32_e64 v72, v72, v232, s[20:21]
	v_cndmask_b32_e64 v71, v71, v232, s[18:19]
	v_cndmask_b32_e64 v70, v70, v232, s[16:17]
	v_cndmask_b32_e64 v69, v69, v232, s[14:15]
	v_cndmask_b32_e64 v68, v68, v232, s[12:13]
	v_cndmask_b32_e64 v67, v67, v232, s[10:11]
	v_cndmask_b32_e64 v66, v66, v232, s[8:9]
	v_cndmask_b32_e64 v65, v65, v232, s[6:7]
	v_cndmask_b32_e32 v64, v64, v232, vcc
.LBB0_1175:
	v_max_f32_e32 v146, v81, v81
	v_max_f32_e32 v147, v80, v80
	v_max_f32_e32 v146, v147, v146
	v_max3_f32 v146, v146, v82, v83
	v_max3_f32 v146, v146, v84, v85
	v_max3_f32 v146, v146, v86, v87
	v_max3_f32 v146, v146, v88, v89
	v_max3_f32 v146, v146, v90, v91
	v_max3_f32 v146, v146, v92, v93
	v_max3_f32 v146, v146, v94, v95
	v_max3_f32 v146, v146, v64, v65
	v_max3_f32 v146, v146, v66, v67
	v_max3_f32 v146, v146, v68, v69
	v_max3_f32 v146, v146, v70, v71
	v_max3_f32 v146, v146, v72, v73
	v_max3_f32 v146, v146, v74, v75
	v_max3_f32 v146, v146, v76, v77
	v_max3_f32 v146, v146, v78, v79
	v_mov_b32_e32 v147, v146
	s_nop 1
	v_permlane32_swap_b32_e32 v146, v147
	v_max_f32_e32 v147, v147, v147
	v_max_f32_e32 v146, v146, v146
	v_max_f32_e32 v146, v146, v147
	v_sub_f32_e32 v147, v146, v187
	v_mul_f32_e32 v147, 0x3db504f3, v147
	s_mov_b32 s6, 0x41000000
	v_cmp_ge_f32_e32 vcc, s6, v147
	v_max_f32_e32 v147, v187, v187
	v_max_f32_e32 v147, v147, v146
	v_sub_f32_e32 v146, v187, v147
	v_mul_f32_e32 v146, 0x3e0293ee, v146
	v_exp_f32_e32 v146, v146
	s_cmp_eq_u64 vcc, exec
	s_cselect_b64 s[6:7], -1, 0
	s_barrier
	s_waitcnt vmcnt(0)
	v_cndmask_b32_e64 v146, v146, 1.0, s[6:7]
	v_cmp_gt_f32_e32 vcc, 1.0, v146
	s_waitcnt vmcnt(0)
	ds_write_b128 v184, v[242:245] offset:16384
	ds_write_b128 v185, v[246:249] offset:16384
	s_cbranch_vccz .LBB0_1179
	s_and_saveexec_b64 s[8:9], s[4:5]
	ds_write_b32 v173, v146 offset:128
	s_or_b64 exec, exec, s[8:9]
	s_waitcnt lgkmcnt(0)
	ds_read_b128 v[130:133], v169 offset:224
	ds_read_b128 v[134:137], v169 offset:192
	ds_read_b128 v[138:141], v169 offset:160
	ds_read_b128 v[142:145], v169 offset:128
	s_waitcnt lgkmcnt(3)
	v_pk_mul_f32 v[62:63], v[62:63], v[132:133]
	s_waitcnt lgkmcnt(2)
	v_pk_mul_f32 v[58:59], v[58:59], v[136:137]
	s_waitcnt lgkmcnt(1)
	v_pk_mul_f32 v[54:55], v[54:55], v[140:141]
	s_waitcnt lgkmcnt(0)
	v_pk_mul_f32 v[50:51], v[50:51], v[144:145]
	v_pk_mul_f32 v[60:61], v[60:61], v[130:131]
	v_pk_mul_f32 v[56:57], v[56:57], v[134:135]
	v_pk_mul_f32 v[52:53], v[52:53], v[138:139]
	v_pk_mul_f32 v[48:49], v[48:49], v[142:143]
	v_pk_mul_f32 v[46:47], v[46:47], v[132:133]
	v_pk_mul_f32 v[42:43], v[42:43], v[136:137]
	v_pk_mul_f32 v[38:39], v[38:39], v[140:141]
	v_pk_mul_f32 v[34:35], v[34:35], v[144:145]
	v_pk_mul_f32 v[44:45], v[44:45], v[130:131]
	v_pk_mul_f32 v[40:41], v[40:41], v[134:135]
	v_pk_mul_f32 v[36:37], v[36:37], v[138:139]
	v_pk_mul_f32 v[32:33], v[32:33], v[142:143]
	v_pk_mul_f32 v[30:31], v[30:31], v[132:133]
	v_pk_mul_f32 v[26:27], v[26:27], v[136:137]
	v_pk_mul_f32 v[22:23], v[22:23], v[140:141]
	v_pk_mul_f32 v[18:19], v[18:19], v[144:145]
	v_pk_mul_f32 v[28:29], v[28:29], v[130:131]
	v_pk_mul_f32 v[24:25], v[24:25], v[134:135]
	v_pk_mul_f32 v[20:21], v[20:21], v[138:139]
	v_pk_mul_f32 v[16:17], v[16:17], v[142:143]
	v_pk_mul_f32 v[14:15], v[14:15], v[132:133]
	v_pk_mul_f32 v[10:11], v[10:11], v[136:137]
	v_pk_mul_f32 v[6:7], v[6:7], v[140:141]
	v_pk_mul_f32 v[2:3], v[2:3], v[144:145]
	v_pk_mul_f32 v[12:13], v[12:13], v[130:131]
	v_pk_mul_f32 v[8:9], v[8:9], v[134:135]
	v_pk_mul_f32 v[4:5], v[4:5], v[138:139]
	v_pk_mul_f32 v[0:1], v[0:1], v[142:143]
